# GEMM K-loops: alternate MFMA groups issue their four B fragments in reverse order (snake)
# speedup vs baseline: 1.0264x; 1.0038x over previous
.LBB0_677:
	s_add_i32 s10, s10, 64
	s_waitcnt lgkmcnt(2)
	v_mfma_f32_16x16x32_bf16 v[162:165], v[202:205], v[178:181], v[162:165]
	v_mfma_f32_16x16x32_bf16 v[154:157], v[202:205], v[182:185], v[154:157]
	v_mfma_f32_16x16x32_bf16 v[134:137], v[202:205], v[186:189], v[134:137]
	v_mfma_f32_16x16x32_bf16 v[114:117], v[202:205], v[190:193], v[114:117]
	ds_read_b128 v[202:205], v216 offset:8192
	s_waitcnt lgkmcnt(2)
	v_mfma_f32_16x16x32_bf16 v[82:85], v[198:201], v[190:193], v[82:85]
	v_mfma_f32_16x16x32_bf16 v[86:89], v[198:201], v[186:189], v[86:89]
	v_mfma_f32_16x16x32_bf16 v[90:93], v[198:201], v[182:185], v[90:93]
	v_mfma_f32_16x16x32_bf16 v[94:97], v[198:201], v[178:181], v[94:97]
	ds_read_b128 v[198:201], v216 offset:10240
	s_waitcnt lgkmcnt(2)
	v_mfma_f32_16x16x32_bf16 v[78:81], v[194:197], v[178:181], v[78:81]
	v_mfma_f32_16x16x32_bf16 v[74:77], v[194:197], v[182:185], v[74:77]
	v_mfma_f32_16x16x32_bf16 v[70:73], v[194:197], v[186:189], v[70:73]
	v_mfma_f32_16x16x32_bf16 v[66:69], v[194:197], v[190:193], v[66:69]
	ds_read_b128 v[194:197], v216 offset:12288
	s_waitcnt lgkmcnt(2)
	v_mfma_f32_16x16x32_bf16 v[50:53], v[202:205], v[190:193], v[50:53]
	v_mfma_f32_16x16x32_bf16 v[54:57], v[202:205], v[186:189], v[54:57]
	v_mfma_f32_16x16x32_bf16 v[58:61], v[202:205], v[182:185], v[58:61]
	v_mfma_f32_16x16x32_bf16 v[62:65], v[202:205], v[178:181], v[62:65]
	ds_read_b128 v[202:205], v216 offset:14336
	s_waitcnt lgkmcnt(2)
	v_mfma_f32_16x16x32_bf16 v[46:49], v[198:201], v[178:181], v[46:49]
	v_mfma_f32_16x16x32_bf16 v[42:45], v[198:201], v[182:185], v[42:45]
	v_mfma_f32_16x16x32_bf16 v[38:41], v[198:201], v[186:189], v[38:41]
	v_mfma_f32_16x16x32_bf16 v[34:37], v[198:201], v[190:193], v[34:37]
	s_waitcnt lgkmcnt(1)
	v_mfma_f32_16x16x32_bf16 v[6:9], v[194:197], v[190:193], v[6:9]
	v_mfma_f32_16x16x32_bf16 v[18:21], v[194:197], v[186:189], v[18:21]
	v_mfma_f32_16x16x32_bf16 v[26:29], v[194:197], v[182:185], v[26:29]
	v_mfma_f32_16x16x32_bf16 v[30:33], v[194:197], v[178:181], v[30:33]
	s_waitcnt lgkmcnt(0)
	v_mfma_f32_16x16x32_bf16 v[22:25], v[202:205], v[178:181], v[22:25]
	v_mfma_f32_16x16x32_bf16 v[14:17], v[202:205], v[182:185], v[14:17]
	v_mfma_f32_16x16x32_bf16 v[10:13], v[202:205], v[186:189], v[10:13]
	v_mfma_f32_16x16x32_bf16 v[2:5], v[202:205], v[190:193], v[2:5]
	s_setprio 0
	s_add_u32 s38, s38, 0x80
	s_addc_u32 s39, s39, 0
	s_add_u32 s40, s40, 0x80
	s_addc_u32 s41, s41, 0
	s_and_b64 vcc, exec, s[52:53]
	s_cbranch_vccnz .LBB0_684

.LBB0_680:
	s_waitcnt lgkmcnt(3)
	v_mfma_f32_16x16x32_bf16 v[158:161], v[178:181], v[238:241], v[158:161]
	v_mfma_f32_16x16x32_bf16 v[166:169], v[178:181], v[218:221], v[166:169]
	v_mfma_f32_16x16x32_bf16 v[170:173], v[178:181], v[198:201], v[170:173]
	v_mfma_f32_16x16x32_bf16 v[174:177], v[178:181], v[194:197], v[174:177]
	s_add_u32 s100, s38, 0x1c3c000
	s_addc_u32 s101, s39, 0
	global_load_dwordx4 v[98:101], v208, s[100:101] offset:128
	v_add_u32_e32 v102, 0x10000, v208
	global_load_dwordx4 v[102:105], v102, s[100:101] offset:128
	ds_read_b128 v[202:205], v216 offset:8192
	s_waitcnt lgkmcnt(3)
	v_mfma_f32_16x16x32_bf16 v[162:165], v[182:185], v[194:197], v[162:165]
	v_mfma_f32_16x16x32_bf16 v[154:157], v[182:185], v[198:201], v[154:157]
	v_mfma_f32_16x16x32_bf16 v[134:137], v[182:185], v[218:221], v[134:137]
	v_mfma_f32_16x16x32_bf16 v[114:117], v[182:185], v[238:241], v[114:117]
	v_add_u32_e32 v106, 0x20000, v208
	global_load_dwordx4 v[106:109], v106, s[100:101] offset:128
	v_add_u32_e32 v110, 0x30000, v208
	global_load_dwordx4 v[110:113], v110, s[100:101] offset:128
	v_add_u32_e32 v217, v214, v212
	ds_read_b128 v[242:245], v216 offset:10240
	ds_read_b128 v[178:181], v217 offset:32768
	s_waitcnt lgkmcnt(4)
	v_mfma_f32_16x16x32_bf16 v[82:85], v[186:189], v[238:241], v[82:85]
	v_mfma_f32_16x16x32_bf16 v[86:89], v[186:189], v[218:221], v[86:89]
	v_mfma_f32_16x16x32_bf16 v[90:93], v[186:189], v[198:201], v[90:93]
	v_mfma_f32_16x16x32_bf16 v[94:97], v[186:189], v[194:197], v[94:97]
	v_add_u32_e32 v118, 0x40000, v208
	global_load_dwordx4 v[118:121], v118, s[100:101] offset:128
	v_add_u32_e32 v122, 0x50000, v208
	global_load_dwordx4 v[122:125], v122, s[100:101] offset:128
	ds_read_b128 v[246:249], v216 offset:12288
	ds_read_b128 v[182:185], v217 offset:34816
	s_waitcnt lgkmcnt(5)
	v_mfma_f32_16x16x32_bf16 v[78:81], v[190:193], v[194:197], v[78:81]
	v_mfma_f32_16x16x32_bf16 v[74:77], v[190:193], v[198:201], v[74:77]
	v_mfma_f32_16x16x32_bf16 v[70:73], v[190:193], v[218:221], v[70:73]
	v_mfma_f32_16x16x32_bf16 v[66:69], v[190:193], v[238:241], v[66:69]
	v_add_u32_e32 v138, 0x60000, v208
	global_load_dwordx4 v[138:141], v138, s[100:101] offset:128
	v_add_u32_e32 v142, 0x70000, v208
	global_load_dwordx4 v[142:145], v142, s[100:101] offset:128
	ds_read_b128 v[226:229], v216 offset:14336
	ds_read_b128 v[186:189], v217 offset:36864
	s_waitcnt lgkmcnt(6)
	v_mfma_f32_16x16x32_bf16 v[50:53], v[202:205], v[238:241], v[50:53]
	v_mfma_f32_16x16x32_bf16 v[54:57], v[202:205], v[218:221], v[54:57]
	v_mfma_f32_16x16x32_bf16 v[58:61], v[202:205], v[198:201], v[58:61]
	v_mfma_f32_16x16x32_bf16 v[62:65], v[202:205], v[194:197], v[62:65]
	s_add_u32 s100, s40, 0xac3c000
	s_addc_u32 s101, s41, 0
	global_load_dwordx4 v[126:129], v208, s[100:101] offset:128
	v_add_u32_e32 v130, 0x10000, v208
	global_load_dwordx4 v[130:133], v130, s[100:101] offset:128
	v_add_u32_e32 v216, v213, v212
	s_waitcnt lgkmcnt(5)
	v_mfma_f32_16x16x32_bf16 v[46:49], v[242:245], v[194:197], v[46:49]
	v_mfma_f32_16x16x32_bf16 v[42:45], v[242:245], v[198:201], v[42:45]
	v_mfma_f32_16x16x32_bf16 v[38:41], v[242:245], v[218:221], v[38:41]
	v_mfma_f32_16x16x32_bf16 v[34:37], v[242:245], v[238:241], v[34:37]
	v_add_u32_e32 v146, 0x20000, v208
	global_load_dwordx4 v[146:149], v146, s[100:101] offset:128
	v_add_u32_e32 v150, 0x30000, v208
	global_load_dwordx4 v[150:153], v150, s[100:101] offset:128
	ds_read_b128 v[242:245], v216
	ds_read_b128 v[190:193], v217 offset:38912
	ds_read_b128 v[202:205], v216 offset:2048
	s_waitcnt lgkmcnt(6)
	v_mfma_f32_16x16x32_bf16 v[6:9], v[246:249], v[238:241], v[6:9]
	v_mfma_f32_16x16x32_bf16 v[18:21], v[246:249], v[218:221], v[18:21]
	v_mfma_f32_16x16x32_bf16 v[26:29], v[246:249], v[198:201], v[26:29]
	v_mfma_f32_16x16x32_bf16 v[30:33], v[246:249], v[194:197], v[30:33]
	s_waitcnt lgkmcnt(4)
	v_mfma_f32_16x16x32_bf16 v[14:17], v[226:229], v[198:201], v[14:17]
	ds_read_b128 v[198:201], v216 offset:4096
	v_mfma_f32_16x16x32_bf16 v[22:25], v[226:229], v[194:197], v[22:25]
	v_mfma_f32_16x16x32_bf16 v[10:13], v[226:229], v[218:221], v[10:13]
	v_mfma_f32_16x16x32_bf16 v[2:5], v[226:229], v[238:241], v[2:5]
	ds_read_b128 v[194:197], v216 offset:6144
	s_waitcnt lgkmcnt(4)
	v_mfma_f32_16x16x32_bf16 v[174:177], v[242:245], v[178:181], v[174:177]
	v_mfma_f32_16x16x32_bf16 v[170:173], v[242:245], v[182:185], v[170:173]
	v_mfma_f32_16x16x32_bf16 v[166:169], v[242:245], v[186:189], v[166:169]
	s_waitcnt lgkmcnt(3)
	v_mfma_f32_16x16x32_bf16 v[158:161], v[242:245], v[190:193], v[158:161]
	s_branch .LBB0_677
.Lpeel_677:
	s_waitcnt lgkmcnt(3)
	v_mfma_f32_16x16x32_bf16 v[174:177], v[178:181], v[194:197], v[174:177]
	v_mfma_f32_16x16x32_bf16 v[170:173], v[178:181], v[198:201], v[170:173]
	v_mfma_f32_16x16x32_bf16 v[166:169], v[178:181], v[218:221], v[166:169]
	v_mfma_f32_16x16x32_bf16 v[158:161], v[178:181], v[238:241], v[158:161]
	ds_read_b128 v[202:205], v216 offset:8192
	s_waitcnt lgkmcnt(3)
	v_mfma_f32_16x16x32_bf16 v[114:117], v[182:185], v[238:241], v[114:117]
	v_mfma_f32_16x16x32_bf16 v[134:137], v[182:185], v[218:221], v[134:137]
	v_mfma_f32_16x16x32_bf16 v[154:157], v[182:185], v[198:201], v[154:157]
	v_mfma_f32_16x16x32_bf16 v[162:165], v[182:185], v[194:197], v[162:165]
	v_add_u32_e32 v217, v214, v212
	ds_read_b128 v[242:245], v216 offset:10240
	ds_read_b128 v[178:181], v217 offset:32768
	s_waitcnt lgkmcnt(4)
	v_mfma_f32_16x16x32_bf16 v[94:97], v[186:189], v[194:197], v[94:97]
	v_mfma_f32_16x16x32_bf16 v[90:93], v[186:189], v[198:201], v[90:93]
	v_mfma_f32_16x16x32_bf16 v[86:89], v[186:189], v[218:221], v[86:89]
	v_mfma_f32_16x16x32_bf16 v[82:85], v[186:189], v[238:241], v[82:85]
	ds_read_b128 v[246:249], v216 offset:12288
	ds_read_b128 v[182:185], v217 offset:34816
	s_waitcnt lgkmcnt(5)
	v_mfma_f32_16x16x32_bf16 v[66:69], v[190:193], v[238:241], v[66:69]
	v_mfma_f32_16x16x32_bf16 v[70:73], v[190:193], v[218:221], v[70:73]
	v_mfma_f32_16x16x32_bf16 v[74:77], v[190:193], v[198:201], v[74:77]
	v_mfma_f32_16x16x32_bf16 v[78:81], v[190:193], v[194:197], v[78:81]
	ds_read_b128 v[226:229], v216 offset:14336
	ds_read_b128 v[186:189], v217 offset:36864
	s_waitcnt lgkmcnt(6)
	v_mfma_f32_16x16x32_bf16 v[62:65], v[202:205], v[194:197], v[62:65]
	v_mfma_f32_16x16x32_bf16 v[58:61], v[202:205], v[198:201], v[58:61]
	v_mfma_f32_16x16x32_bf16 v[54:57], v[202:205], v[218:221], v[54:57]
	v_mfma_f32_16x16x32_bf16 v[50:53], v[202:205], v[238:241], v[50:53]
	v_add_u32_e32 v216, v213, v212
	s_waitcnt lgkmcnt(5)
	v_mfma_f32_16x16x32_bf16 v[34:37], v[242:245], v[238:241], v[34:37]
	v_mfma_f32_16x16x32_bf16 v[38:41], v[242:245], v[218:221], v[38:41]
	v_mfma_f32_16x16x32_bf16 v[42:45], v[242:245], v[198:201], v[42:45]
	v_mfma_f32_16x16x32_bf16 v[46:49], v[242:245], v[194:197], v[46:49]
	ds_read_b128 v[242:245], v216
	ds_read_b128 v[190:193], v217 offset:38912
	ds_read_b128 v[202:205], v216 offset:2048
	s_waitcnt lgkmcnt(6)
	v_mfma_f32_16x16x32_bf16 v[30:33], v[246:249], v[194:197], v[30:33]
	v_mfma_f32_16x16x32_bf16 v[26:29], v[246:249], v[198:201], v[26:29]
	v_mfma_f32_16x16x32_bf16 v[18:21], v[246:249], v[218:221], v[18:21]
	v_mfma_f32_16x16x32_bf16 v[6:9], v[246:249], v[238:241], v[6:9]
	s_waitcnt lgkmcnt(4)
	v_mfma_f32_16x16x32_bf16 v[14:17], v[226:229], v[198:201], v[14:17]
	ds_read_b128 v[198:201], v216 offset:4096
	v_mfma_f32_16x16x32_bf16 v[22:25], v[226:229], v[194:197], v[22:25]
	v_mfma_f32_16x16x32_bf16 v[10:13], v[226:229], v[218:221], v[10:13]
	v_mfma_f32_16x16x32_bf16 v[2:5], v[226:229], v[238:241], v[2:5]
	ds_read_b128 v[194:197], v216 offset:6144
	s_waitcnt lgkmcnt(4)
	v_mfma_f32_16x16x32_bf16 v[174:177], v[242:245], v[178:181], v[174:177]
	v_mfma_f32_16x16x32_bf16 v[170:173], v[242:245], v[182:185], v[170:173]
	v_mfma_f32_16x16x32_bf16 v[166:169], v[242:245], v[186:189], v[166:169]
	s_waitcnt lgkmcnt(3)
	v_mfma_f32_16x16x32_bf16 v[158:161], v[242:245], v[190:193], v[158:161]
	s_add_i32 s10, s10, 64
	s_waitcnt lgkmcnt(2)
	v_mfma_f32_16x16x32_bf16 v[114:117], v[202:205], v[190:193], v[114:117]
	v_mfma_f32_16x16x32_bf16 v[134:137], v[202:205], v[186:189], v[134:137]
	v_mfma_f32_16x16x32_bf16 v[154:157], v[202:205], v[182:185], v[154:157]
	v_mfma_f32_16x16x32_bf16 v[162:165], v[202:205], v[178:181], v[162:165]
	ds_read_b128 v[202:205], v216 offset:8192
	s_waitcnt lgkmcnt(2)
	v_mfma_f32_16x16x32_bf16 v[94:97], v[198:201], v[178:181], v[94:97]
	v_mfma_f32_16x16x32_bf16 v[90:93], v[198:201], v[182:185], v[90:93]
	v_mfma_f32_16x16x32_bf16 v[86:89], v[198:201], v[186:189], v[86:89]
	v_mfma_f32_16x16x32_bf16 v[82:85], v[198:201], v[190:193], v[82:85]
	ds_read_b128 v[198:201], v216 offset:10240
	s_waitcnt lgkmcnt(2)
	v_mfma_f32_16x16x32_bf16 v[66:69], v[194:197], v[190:193], v[66:69]
	v_mfma_f32_16x16x32_bf16 v[70:73], v[194:197], v[186:189], v[70:73]
	v_mfma_f32_16x16x32_bf16 v[74:77], v[194:197], v[182:185], v[74:77]
	v_mfma_f32_16x16x32_bf16 v[78:81], v[194:197], v[178:181], v[78:81]
	ds_read_b128 v[194:197], v216 offset:12288
	s_waitcnt lgkmcnt(2)
	v_mfma_f32_16x16x32_bf16 v[62:65], v[202:205], v[178:181], v[62:65]
	v_mfma_f32_16x16x32_bf16 v[58:61], v[202:205], v[182:185], v[58:61]
	v_mfma_f32_16x16x32_bf16 v[54:57], v[202:205], v[186:189], v[54:57]
	v_mfma_f32_16x16x32_bf16 v[50:53], v[202:205], v[190:193], v[50:53]
	ds_read_b128 v[202:205], v216 offset:14336
	s_waitcnt lgkmcnt(2)
	v_mfma_f32_16x16x32_bf16 v[34:37], v[198:201], v[190:193], v[34:37]
	v_mfma_f32_16x16x32_bf16 v[38:41], v[198:201], v[186:189], v[38:41]
	v_mfma_f32_16x16x32_bf16 v[42:45], v[198:201], v[182:185], v[42:45]
	v_mfma_f32_16x16x32_bf16 v[46:49], v[198:201], v[178:181], v[46:49]
	s_waitcnt lgkmcnt(1)
	v_mfma_f32_16x16x32_bf16 v[30:33], v[194:197], v[178:181], v[30:33]
	v_mfma_f32_16x16x32_bf16 v[26:29], v[194:197], v[182:185], v[26:29]
	v_mfma_f32_16x16x32_bf16 v[18:21], v[194:197], v[186:189], v[18:21]
	v_mfma_f32_16x16x32_bf16 v[6:9], v[194:197], v[190:193], v[6:9]
	s_waitcnt lgkmcnt(0)
	v_mfma_f32_16x16x32_bf16 v[2:5], v[202:205], v[190:193], v[2:5]
	v_mfma_f32_16x16x32_bf16 v[10:13], v[202:205], v[186:189], v[10:13]
	v_mfma_f32_16x16x32_bf16 v[14:17], v[202:205], v[182:185], v[14:17]
	v_mfma_f32_16x16x32_bf16 v[22:25], v[202:205], v[178:181], v[22:25]
	s_setprio 0
	s_branch .LBB0_684

.LBB0_1483:
	s_add_i32 s1, s1, 64
	s_waitcnt lgkmcnt(2)
	v_mfma_f32_16x16x32_bf16 v[162:165], v[202:205], v[178:181], v[162:165]
	v_mfma_f32_16x16x32_bf16 v[154:157], v[202:205], v[182:185], v[154:157]
	v_mfma_f32_16x16x32_bf16 v[122:125], v[202:205], v[186:189], v[122:125]
	v_mfma_f32_16x16x32_bf16 v[106:109], v[202:205], v[190:193], v[106:109]
	ds_read_b128 v[202:205], v216 offset:8192
	s_waitcnt lgkmcnt(2)
	v_mfma_f32_16x16x32_bf16 v[82:85], v[198:201], v[190:193], v[82:85]
	v_mfma_f32_16x16x32_bf16 v[86:89], v[198:201], v[186:189], v[86:89]
	v_mfma_f32_16x16x32_bf16 v[90:93], v[198:201], v[182:185], v[90:93]
	v_mfma_f32_16x16x32_bf16 v[94:97], v[198:201], v[178:181], v[94:97]
	ds_read_b128 v[198:201], v216 offset:10240
	s_waitcnt lgkmcnt(2)
	v_mfma_f32_16x16x32_bf16 v[78:81], v[194:197], v[178:181], v[78:81]
	v_mfma_f32_16x16x32_bf16 v[74:77], v[194:197], v[182:185], v[74:77]
	v_mfma_f32_16x16x32_bf16 v[70:73], v[194:197], v[186:189], v[70:73]
	v_mfma_f32_16x16x32_bf16 v[66:69], v[194:197], v[190:193], v[66:69]
	ds_read_b128 v[194:197], v216 offset:12288
	s_waitcnt lgkmcnt(2)
	v_mfma_f32_16x16x32_bf16 v[50:53], v[202:205], v[190:193], v[50:53]
	v_mfma_f32_16x16x32_bf16 v[54:57], v[202:205], v[186:189], v[54:57]
	v_mfma_f32_16x16x32_bf16 v[58:61], v[202:205], v[182:185], v[58:61]
	v_mfma_f32_16x16x32_bf16 v[62:65], v[202:205], v[178:181], v[62:65]
	ds_read_b128 v[202:205], v216 offset:14336
	s_waitcnt lgkmcnt(2)
	v_mfma_f32_16x16x32_bf16 v[46:49], v[198:201], v[178:181], v[46:49]
	v_mfma_f32_16x16x32_bf16 v[42:45], v[198:201], v[182:185], v[42:45]
	v_mfma_f32_16x16x32_bf16 v[38:41], v[198:201], v[186:189], v[38:41]
	v_mfma_f32_16x16x32_bf16 v[34:37], v[198:201], v[190:193], v[34:37]
	s_waitcnt lgkmcnt(1)
	v_mfma_f32_16x16x32_bf16 v[6:9], v[194:197], v[190:193], v[6:9]
	v_mfma_f32_16x16x32_bf16 v[18:21], v[194:197], v[186:189], v[18:21]
	v_mfma_f32_16x16x32_bf16 v[26:29], v[194:197], v[182:185], v[26:29]
	v_mfma_f32_16x16x32_bf16 v[30:33], v[194:197], v[178:181], v[30:33]
	s_waitcnt lgkmcnt(0)
	v_mfma_f32_16x16x32_bf16 v[22:25], v[202:205], v[178:181], v[22:25]
	v_mfma_f32_16x16x32_bf16 v[14:17], v[202:205], v[182:185], v[14:17]
	v_mfma_f32_16x16x32_bf16 v[10:13], v[202:205], v[186:189], v[10:13]
	v_mfma_f32_16x16x32_bf16 v[2:5], v[202:205], v[190:193], v[2:5]
	s_setprio 0
	s_add_u32 s38, s38, 0x80
	s_addc_u32 s39, s39, 0
	s_add_u32 s40, s40, 0x80
	s_addc_u32 s41, s41, 0
	s_and_b64 vcc, exec, s[44:45]
	s_cbranch_vccnz .LBB0_1490

.LBB0_1486:
	s_waitcnt lgkmcnt(3)
	v_mfma_f32_16x16x32_bf16 v[158:161], v[178:181], v[226:229], v[158:161]
	v_mfma_f32_16x16x32_bf16 v[166:169], v[178:181], v[218:221], v[166:169]
	v_mfma_f32_16x16x32_bf16 v[170:173], v[178:181], v[198:201], v[170:173]
	v_mfma_f32_16x16x32_bf16 v[174:177], v[178:181], v[194:197], v[174:177]
	s_add_u32 s100, s38, 0x1c3c000
	s_addc_u32 s101, s39, 0
	global_load_dwordx4 v[98:101], v208, s[100:101] offset:128
	v_add_u32_e32 v102, 0x10000, v208
	global_load_dwordx4 v[102:105], v102, s[100:101] offset:128
	ds_read_b128 v[202:205], v216 offset:8192
	s_waitcnt lgkmcnt(3)
	v_mfma_f32_16x16x32_bf16 v[162:165], v[182:185], v[194:197], v[162:165]
	v_mfma_f32_16x16x32_bf16 v[154:157], v[182:185], v[198:201], v[154:157]
	v_mfma_f32_16x16x32_bf16 v[122:125], v[182:185], v[218:221], v[122:125]
	v_mfma_f32_16x16x32_bf16 v[106:109], v[182:185], v[226:229], v[106:109]
	v_add_u32_e32 v110, 0x20000, v208
	global_load_dwordx4 v[110:113], v110, s[100:101] offset:128
	v_add_u32_e32 v114, 0x30000, v208
	global_load_dwordx4 v[114:117], v114, s[100:101] offset:128
	v_add_u32_e32 v217, v214, v212
	ds_read_b128 v[238:241], v216 offset:10240
	ds_read_b128 v[178:181], v217 offset:32768
	s_waitcnt lgkmcnt(4)
	v_mfma_f32_16x16x32_bf16 v[82:85], v[186:189], v[226:229], v[82:85]
	v_mfma_f32_16x16x32_bf16 v[86:89], v[186:189], v[218:221], v[86:89]
	v_mfma_f32_16x16x32_bf16 v[90:93], v[186:189], v[198:201], v[90:93]
	v_mfma_f32_16x16x32_bf16 v[94:97], v[186:189], v[194:197], v[94:97]
	v_add_u32_e32 v118, 0x40000, v208
	global_load_dwordx4 v[118:121], v118, s[100:101] offset:128
	v_add_u32_e32 v130, 0x50000, v208
	global_load_dwordx4 v[130:133], v130, s[100:101] offset:128
	ds_read_b128 v[242:245], v216 offset:12288
	ds_read_b128 v[182:185], v217 offset:34816
	s_waitcnt lgkmcnt(5)
	v_mfma_f32_16x16x32_bf16 v[78:81], v[190:193], v[194:197], v[78:81]
	v_mfma_f32_16x16x32_bf16 v[74:77], v[190:193], v[198:201], v[74:77]
	v_mfma_f32_16x16x32_bf16 v[70:73], v[190:193], v[218:221], v[70:73]
	v_mfma_f32_16x16x32_bf16 v[66:69], v[190:193], v[226:229], v[66:69]
	v_add_u32_e32 v138, 0x60000, v208
	global_load_dwordx4 v[138:141], v138, s[100:101] offset:128
	v_add_u32_e32 v146, 0x70000, v208
	global_load_dwordx4 v[146:149], v146, s[100:101] offset:128
	ds_read_b128 v[246:249], v216 offset:14336
	ds_read_b128 v[186:189], v217 offset:36864
	s_waitcnt lgkmcnt(6)
	v_mfma_f32_16x16x32_bf16 v[50:53], v[202:205], v[226:229], v[50:53]
	v_mfma_f32_16x16x32_bf16 v[54:57], v[202:205], v[218:221], v[54:57]
	v_mfma_f32_16x16x32_bf16 v[58:61], v[202:205], v[198:201], v[58:61]
	v_mfma_f32_16x16x32_bf16 v[62:65], v[202:205], v[194:197], v[62:65]
	s_add_u32 s100, s40, 0xb34c000
	s_addc_u32 s101, s41, 0
	global_load_dwordx4 v[126:129], v208, s[100:101] offset:128
	v_add_u32_e32 v134, 0x10000, v208
	global_load_dwordx4 v[134:137], v134, s[100:101] offset:128
	v_add_u32_e32 v216, v213, v212
	s_waitcnt lgkmcnt(5)
	v_mfma_f32_16x16x32_bf16 v[46:49], v[238:241], v[194:197], v[46:49]
	v_mfma_f32_16x16x32_bf16 v[42:45], v[238:241], v[198:201], v[42:45]
	v_mfma_f32_16x16x32_bf16 v[38:41], v[238:241], v[218:221], v[38:41]
	v_mfma_f32_16x16x32_bf16 v[34:37], v[238:241], v[226:229], v[34:37]
	v_add_u32_e32 v142, 0x20000, v208
	global_load_dwordx4 v[142:145], v142, s[100:101] offset:128
	v_add_u32_e32 v150, 0x30000, v208
	global_load_dwordx4 v[150:153], v150, s[100:101] offset:128
	ds_read_b128 v[238:241], v216
	ds_read_b128 v[190:193], v217 offset:38912
	ds_read_b128 v[202:205], v216 offset:2048
	s_waitcnt lgkmcnt(6)
	v_mfma_f32_16x16x32_bf16 v[6:9], v[242:245], v[226:229], v[6:9]
	v_mfma_f32_16x16x32_bf16 v[18:21], v[242:245], v[218:221], v[18:21]
	v_mfma_f32_16x16x32_bf16 v[26:29], v[242:245], v[198:201], v[26:29]
	v_mfma_f32_16x16x32_bf16 v[30:33], v[242:245], v[194:197], v[30:33]
	s_waitcnt lgkmcnt(4)
	v_mfma_f32_16x16x32_bf16 v[14:17], v[246:249], v[198:201], v[14:17]
	ds_read_b128 v[198:201], v216 offset:4096
	v_mfma_f32_16x16x32_bf16 v[22:25], v[246:249], v[194:197], v[22:25]
	v_mfma_f32_16x16x32_bf16 v[10:13], v[246:249], v[218:221], v[10:13]
	v_mfma_f32_16x16x32_bf16 v[2:5], v[246:249], v[226:229], v[2:5]
	ds_read_b128 v[194:197], v216 offset:6144
	s_waitcnt lgkmcnt(4)
	v_mfma_f32_16x16x32_bf16 v[174:177], v[238:241], v[178:181], v[174:177]
	v_mfma_f32_16x16x32_bf16 v[170:173], v[238:241], v[182:185], v[170:173]
	v_mfma_f32_16x16x32_bf16 v[166:169], v[238:241], v[186:189], v[166:169]
	s_waitcnt lgkmcnt(3)
	v_mfma_f32_16x16x32_bf16 v[158:161], v[238:241], v[190:193], v[158:161]
	s_branch .LBB0_1483
.Lpeel_1483:
	s_waitcnt lgkmcnt(3)
	v_mfma_f32_16x16x32_bf16 v[174:177], v[178:181], v[194:197], v[174:177]
	v_mfma_f32_16x16x32_bf16 v[170:173], v[178:181], v[198:201], v[170:173]
	v_mfma_f32_16x16x32_bf16 v[166:169], v[178:181], v[218:221], v[166:169]
	v_mfma_f32_16x16x32_bf16 v[158:161], v[178:181], v[226:229], v[158:161]
	ds_read_b128 v[202:205], v216 offset:8192
	s_waitcnt lgkmcnt(3)
	v_mfma_f32_16x16x32_bf16 v[106:109], v[182:185], v[226:229], v[106:109]
	v_mfma_f32_16x16x32_bf16 v[122:125], v[182:185], v[218:221], v[122:125]
	v_mfma_f32_16x16x32_bf16 v[154:157], v[182:185], v[198:201], v[154:157]
	v_mfma_f32_16x16x32_bf16 v[162:165], v[182:185], v[194:197], v[162:165]
	v_add_u32_e32 v217, v214, v212
	ds_read_b128 v[238:241], v216 offset:10240
	ds_read_b128 v[178:181], v217 offset:32768
	s_waitcnt lgkmcnt(4)
	v_mfma_f32_16x16x32_bf16 v[94:97], v[186:189], v[194:197], v[94:97]
	v_mfma_f32_16x16x32_bf16 v[90:93], v[186:189], v[198:201], v[90:93]
	v_mfma_f32_16x16x32_bf16 v[86:89], v[186:189], v[218:221], v[86:89]
	v_mfma_f32_16x16x32_bf16 v[82:85], v[186:189], v[226:229], v[82:85]
	ds_read_b128 v[242:245], v216 offset:12288
	ds_read_b128 v[182:185], v217 offset:34816
	s_waitcnt lgkmcnt(5)
	v_mfma_f32_16x16x32_bf16 v[66:69], v[190:193], v[226:229], v[66:69]
	v_mfma_f32_16x16x32_bf16 v[70:73], v[190:193], v[218:221], v[70:73]
	v_mfma_f32_16x16x32_bf16 v[74:77], v[190:193], v[198:201], v[74:77]
	v_mfma_f32_16x16x32_bf16 v[78:81], v[190:193], v[194:197], v[78:81]
	ds_read_b128 v[246:249], v216 offset:14336
	ds_read_b128 v[186:189], v217 offset:36864
	s_waitcnt lgkmcnt(6)
	v_mfma_f32_16x16x32_bf16 v[62:65], v[202:205], v[194:197], v[62:65]
	v_mfma_f32_16x16x32_bf16 v[58:61], v[202:205], v[198:201], v[58:61]
	v_mfma_f32_16x16x32_bf16 v[54:57], v[202:205], v[218:221], v[54:57]
	v_mfma_f32_16x16x32_bf16 v[50:53], v[202:205], v[226:229], v[50:53]
	v_add_u32_e32 v216, v213, v212
	s_waitcnt lgkmcnt(5)
	v_mfma_f32_16x16x32_bf16 v[34:37], v[238:241], v[226:229], v[34:37]
	v_mfma_f32_16x16x32_bf16 v[38:41], v[238:241], v[218:221], v[38:41]
	v_mfma_f32_16x16x32_bf16 v[42:45], v[238:241], v[198:201], v[42:45]
	v_mfma_f32_16x16x32_bf16 v[46:49], v[238:241], v[194:197], v[46:49]
	ds_read_b128 v[238:241], v216
	ds_read_b128 v[190:193], v217 offset:38912
	ds_read_b128 v[202:205], v216 offset:2048
	s_waitcnt lgkmcnt(6)
	v_mfma_f32_16x16x32_bf16 v[30:33], v[242:245], v[194:197], v[30:33]
	v_mfma_f32_16x16x32_bf16 v[26:29], v[242:245], v[198:201], v[26:29]
	v_mfma_f32_16x16x32_bf16 v[18:21], v[242:245], v[218:221], v[18:21]
	v_mfma_f32_16x16x32_bf16 v[6:9], v[242:245], v[226:229], v[6:9]
	s_waitcnt lgkmcnt(4)
	v_mfma_f32_16x16x32_bf16 v[14:17], v[246:249], v[198:201], v[14:17]
	ds_read_b128 v[198:201], v216 offset:4096
	v_mfma_f32_16x16x32_bf16 v[22:25], v[246:249], v[194:197], v[22:25]
	v_mfma_f32_16x16x32_bf16 v[10:13], v[246:249], v[218:221], v[10:13]
	v_mfma_f32_16x16x32_bf16 v[2:5], v[246:249], v[226:229], v[2:5]
	ds_read_b128 v[194:197], v216 offset:6144
	s_waitcnt lgkmcnt(4)
	v_mfma_f32_16x16x32_bf16 v[174:177], v[238:241], v[178:181], v[174:177]
	v_mfma_f32_16x16x32_bf16 v[170:173], v[238:241], v[182:185], v[170:173]
	v_mfma_f32_16x16x32_bf16 v[166:169], v[238:241], v[186:189], v[166:169]
	s_waitcnt lgkmcnt(3)
	v_mfma_f32_16x16x32_bf16 v[158:161], v[238:241], v[190:193], v[158:161]
	s_add_i32 s1, s1, 64
	s_waitcnt lgkmcnt(2)
	v_mfma_f32_16x16x32_bf16 v[106:109], v[202:205], v[190:193], v[106:109]
	v_mfma_f32_16x16x32_bf16 v[122:125], v[202:205], v[186:189], v[122:125]
	v_mfma_f32_16x16x32_bf16 v[154:157], v[202:205], v[182:185], v[154:157]
	v_mfma_f32_16x16x32_bf16 v[162:165], v[202:205], v[178:181], v[162:165]
	ds_read_b128 v[202:205], v216 offset:8192
	s_waitcnt lgkmcnt(2)
	v_mfma_f32_16x16x32_bf16 v[94:97], v[198:201], v[178:181], v[94:97]
	v_mfma_f32_16x16x32_bf16 v[90:93], v[198:201], v[182:185], v[90:93]
	v_mfma_f32_16x16x32_bf16 v[86:89], v[198:201], v[186:189], v[86:89]
	v_mfma_f32_16x16x32_bf16 v[82:85], v[198:201], v[190:193], v[82:85]
	ds_read_b128 v[198:201], v216 offset:10240
	s_waitcnt lgkmcnt(2)
	v_mfma_f32_16x16x32_bf16 v[66:69], v[194:197], v[190:193], v[66:69]
	v_mfma_f32_16x16x32_bf16 v[70:73], v[194:197], v[186:189], v[70:73]
	v_mfma_f32_16x16x32_bf16 v[74:77], v[194:197], v[182:185], v[74:77]
	v_mfma_f32_16x16x32_bf16 v[78:81], v[194:197], v[178:181], v[78:81]
	ds_read_b128 v[194:197], v216 offset:12288
	s_waitcnt lgkmcnt(2)
	v_mfma_f32_16x16x32_bf16 v[62:65], v[202:205], v[178:181], v[62:65]
	v_mfma_f32_16x16x32_bf16 v[58:61], v[202:205], v[182:185], v[58:61]
	v_mfma_f32_16x16x32_bf16 v[54:57], v[202:205], v[186:189], v[54:57]
	v_mfma_f32_16x16x32_bf16 v[50:53], v[202:205], v[190:193], v[50:53]
	ds_read_b128 v[202:205], v216 offset:14336
	s_waitcnt lgkmcnt(2)
	v_mfma_f32_16x16x32_bf16 v[34:37], v[198:201], v[190:193], v[34:37]
	v_mfma_f32_16x16x32_bf16 v[38:41], v[198:201], v[186:189], v[38:41]
	v_mfma_f32_16x16x32_bf16 v[42:45], v[198:201], v[182:185], v[42:45]
	v_mfma_f32_16x16x32_bf16 v[46:49], v[198:201], v[178:181], v[46:49]
	s_waitcnt lgkmcnt(1)
	v_mfma_f32_16x16x32_bf16 v[30:33], v[194:197], v[178:181], v[30:33]
	v_mfma_f32_16x16x32_bf16 v[26:29], v[194:197], v[182:185], v[26:29]
	v_mfma_f32_16x16x32_bf16 v[18:21], v[194:197], v[186:189], v[18:21]
	v_mfma_f32_16x16x32_bf16 v[6:9], v[194:197], v[190:193], v[6:9]
	s_waitcnt lgkmcnt(0)
	v_mfma_f32_16x16x32_bf16 v[2:5], v[202:205], v[190:193], v[2:5]
	v_mfma_f32_16x16x32_bf16 v[10:13], v[202:205], v[186:189], v[10:13]
	v_mfma_f32_16x16x32_bf16 v[14:17], v[202:205], v[182:185], v[14:17]
	v_mfma_f32_16x16x32_bf16 v[22:25], v[202:205], v[178:181], v[22:25]
	s_setprio 0
	s_branch .LBB0_1490

.LBB0_1681:
	s_waitcnt lgkmcnt(2)
	v_mfma_f32_16x16x32_bf16 v[162:165], v[202:205], v[178:181], v[162:165]
	v_mfma_f32_16x16x32_bf16 v[166:169], v[202:205], v[182:185], v[166:169]
	v_mfma_f32_16x16x32_bf16 v[170:173], v[202:205], v[186:189], v[170:173]
	v_mfma_f32_16x16x32_bf16 v[174:177], v[202:205], v[190:193], v[174:177]
	ds_read_b128 v[202:205], v217 offset:8192
	s_waitcnt lgkmcnt(2)
	v_mfma_f32_16x16x32_bf16 v[158:161], v[198:201], v[190:193], v[158:161]
	v_mfma_f32_16x16x32_bf16 v[154:157], v[198:201], v[186:189], v[154:157]
	v_mfma_f32_16x16x32_bf16 v[150:153], v[198:201], v[182:185], v[150:153]
	v_mfma_f32_16x16x32_bf16 v[146:149], v[198:201], v[178:181], v[146:149]
	ds_read_b128 v[198:201], v217 offset:10240
	s_waitcnt lgkmcnt(2)
	v_mfma_f32_16x16x32_bf16 v[118:121], v[194:197], v[178:181], v[118:121]
	v_mfma_f32_16x16x32_bf16 v[122:125], v[194:197], v[182:185], v[122:125]
	v_mfma_f32_16x16x32_bf16 v[126:129], v[194:197], v[186:189], v[126:129]
	v_mfma_f32_16x16x32_bf16 v[130:133], v[194:197], v[190:193], v[130:133]
	ds_read_b128 v[194:197], v217 offset:12288
	s_waitcnt lgkmcnt(2)
	v_mfma_f32_16x16x32_bf16 v[110:113], v[202:205], v[190:193], v[110:113]
	v_mfma_f32_16x16x32_bf16 v[106:109], v[202:205], v[186:189], v[106:109]
	v_mfma_f32_16x16x32_bf16 v[102:105], v[202:205], v[182:185], v[102:105]
	v_mfma_f32_16x16x32_bf16 v[98:101], v[202:205], v[178:181], v[98:101]
	ds_read_b128 v[202:205], v217 offset:14336
	s_waitcnt lgkmcnt(2)
	v_mfma_f32_16x16x32_bf16 v[82:85], v[198:201], v[178:181], v[82:85]
	v_mfma_f32_16x16x32_bf16 v[86:89], v[198:201], v[182:185], v[86:89]
	v_mfma_f32_16x16x32_bf16 v[90:93], v[198:201], v[186:189], v[90:93]
	v_mfma_f32_16x16x32_bf16 v[94:97], v[198:201], v[190:193], v[94:97]
	s_waitcnt lgkmcnt(1)
	v_mfma_f32_16x16x32_bf16 v[78:81], v[194:197], v[190:193], v[78:81]
	v_mfma_f32_16x16x32_bf16 v[74:77], v[194:197], v[186:189], v[74:77]
	v_mfma_f32_16x16x32_bf16 v[70:73], v[194:197], v[182:185], v[70:73]
	v_mfma_f32_16x16x32_bf16 v[66:69], v[194:197], v[178:181], v[66:69]
	s_waitcnt lgkmcnt(0)
	v_mfma_f32_16x16x32_bf16 v[50:53], v[202:205], v[178:181], v[50:53]
	v_mfma_f32_16x16x32_bf16 v[54:57], v[202:205], v[182:185], v[54:57]
	v_mfma_f32_16x16x32_bf16 v[58:61], v[202:205], v[186:189], v[58:61]
	v_mfma_f32_16x16x32_bf16 v[62:65], v[202:205], v[190:193], v[62:65]
	s_setprio 0
	s_add_u32 s36, s36, 0x80
	s_addc_u32 s37, s37, 0
	s_add_u32 s38, s38, 0x80
	s_addc_u32 s39, s39, 0
	s_cmpk_gt_u32 s1, 0x3bf
	s_cbranch_scc1 .LBB0_1686

.LBB0_1684:
	s_waitcnt lgkmcnt(3)
	v_mfma_f32_16x16x32_bf16 v[142:145], v[178:181], v[226:229], v[142:145]
	v_mfma_f32_16x16x32_bf16 v[138:141], v[178:181], v[218:221], v[138:141]
	v_mfma_f32_16x16x32_bf16 v[134:137], v[178:181], v[198:201], v[134:137]
	v_mfma_f32_16x16x32_bf16 v[114:117], v[178:181], v[194:197], v[114:117]
	s_add_u32 s100, s36, 0x1c3b000
	s_addc_u32 s101, s37, 0
	global_load_dwordx4 v[2:5], v208, s[100:101] offset:2176
	v_add_u32_e32 v6, 0x10000, v208
	global_load_dwordx4 v[6:9], v6, s[100:101] offset:2176
	ds_read_b128 v[202:205], v217 offset:8192
	s_waitcnt lgkmcnt(3)
	v_mfma_f32_16x16x32_bf16 v[162:165], v[182:185], v[194:197], v[162:165]
	v_mfma_f32_16x16x32_bf16 v[166:169], v[182:185], v[198:201], v[166:169]
	v_mfma_f32_16x16x32_bf16 v[170:173], v[182:185], v[218:221], v[170:173]
	v_mfma_f32_16x16x32_bf16 v[174:177], v[182:185], v[226:229], v[174:177]
	v_add_u32_e32 v10, 0x20000, v208
	global_load_dwordx4 v[10:13], v10, s[100:101] offset:2176
	v_add_u32_e32 v14, 0x30000, v208
	global_load_dwordx4 v[14:17], v14, s[100:101] offset:2176
	v_add_u32_e32 v222, v215, v213
	ds_read_b128 v[238:241], v217 offset:10240
	ds_read_b128 v[178:181], v222 offset:32768
	s_waitcnt lgkmcnt(4)
	v_mfma_f32_16x16x32_bf16 v[158:161], v[186:189], v[226:229], v[158:161]
	v_mfma_f32_16x16x32_bf16 v[154:157], v[186:189], v[218:221], v[154:157]
	v_mfma_f32_16x16x32_bf16 v[150:153], v[186:189], v[198:201], v[150:153]
	v_mfma_f32_16x16x32_bf16 v[146:149], v[186:189], v[194:197], v[146:149]
	v_add_u32_e32 v18, 0x40000, v208
	global_load_dwordx4 v[18:21], v18, s[100:101] offset:2176
	v_add_u32_e32 v26, 0x50000, v208
	global_load_dwordx4 v[26:29], v26, s[100:101] offset:2176
	ds_read_b128 v[242:245], v217 offset:12288
	ds_read_b128 v[182:185], v222 offset:34816
	s_waitcnt lgkmcnt(5)
	v_mfma_f32_16x16x32_bf16 v[118:121], v[190:193], v[194:197], v[118:121]
	v_mfma_f32_16x16x32_bf16 v[122:125], v[190:193], v[198:201], v[122:125]
	v_mfma_f32_16x16x32_bf16 v[126:129], v[190:193], v[218:221], v[126:129]
	v_mfma_f32_16x16x32_bf16 v[130:133], v[190:193], v[226:229], v[130:133]
	v_add_u32_e32 v34, 0x60000, v208
	global_load_dwordx4 v[34:37], v34, s[100:101] offset:2176
	v_add_u32_e32 v42, 0x70000, v208
	global_load_dwordx4 v[42:45], v42, s[100:101] offset:2176
	ds_read_b128 v[246:249], v217 offset:14336
	ds_read_b128 v[186:189], v222 offset:36864
	s_waitcnt lgkmcnt(6)
	v_mfma_f32_16x16x32_bf16 v[110:113], v[202:205], v[226:229], v[110:113]
	v_mfma_f32_16x16x32_bf16 v[106:109], v[202:205], v[218:221], v[106:109]
	v_mfma_f32_16x16x32_bf16 v[102:105], v[202:205], v[198:201], v[102:105]
	v_mfma_f32_16x16x32_bf16 v[98:101], v[202:205], v[194:197], v[98:101]
	s_add_u32 s100, s38, 0xb54c000
	s_addc_u32 s101, s39, 0
	global_load_dwordx4 v[22:25], v208, s[100:101] offset:128
	v_add_u32_e32 v30, 0x10000, v208
	global_load_dwordx4 v[30:33], v30, s[100:101] offset:128
	v_add_u32_e32 v217, v214, v213
	s_waitcnt lgkmcnt(5)
	v_mfma_f32_16x16x32_bf16 v[82:85], v[238:241], v[194:197], v[82:85]
	v_mfma_f32_16x16x32_bf16 v[86:89], v[238:241], v[198:201], v[86:89]
	v_mfma_f32_16x16x32_bf16 v[90:93], v[238:241], v[218:221], v[90:93]
	v_mfma_f32_16x16x32_bf16 v[94:97], v[238:241], v[226:229], v[94:97]
	v_add_u32_e32 v38, 0x20000, v208
	global_load_dwordx4 v[38:41], v38, s[100:101] offset:128
	v_add_u32_e32 v46, 0x30000, v208
	global_load_dwordx4 v[46:49], v46, s[100:101] offset:128
	ds_read_b128 v[238:241], v217
	ds_read_b128 v[190:193], v222 offset:38912
	ds_read_b128 v[202:205], v217 offset:2048
	s_waitcnt lgkmcnt(6)
	v_mfma_f32_16x16x32_bf16 v[78:81], v[242:245], v[226:229], v[78:81]
	v_mfma_f32_16x16x32_bf16 v[74:77], v[242:245], v[218:221], v[74:77]
	v_mfma_f32_16x16x32_bf16 v[70:73], v[242:245], v[198:201], v[70:73]
	v_mfma_f32_16x16x32_bf16 v[66:69], v[242:245], v[194:197], v[66:69]
	s_waitcnt lgkmcnt(4)
	v_mfma_f32_16x16x32_bf16 v[54:57], v[246:249], v[198:201], v[54:57]
	ds_read_b128 v[198:201], v217 offset:4096
	v_mfma_f32_16x16x32_bf16 v[50:53], v[246:249], v[194:197], v[50:53]
	v_mfma_f32_16x16x32_bf16 v[58:61], v[246:249], v[218:221], v[58:61]
	v_mfma_f32_16x16x32_bf16 v[62:65], v[246:249], v[226:229], v[62:65]
	ds_read_b128 v[194:197], v217 offset:6144
	s_waitcnt lgkmcnt(4)
	v_mfma_f32_16x16x32_bf16 v[114:117], v[238:241], v[178:181], v[114:117]
	v_mfma_f32_16x16x32_bf16 v[134:137], v[238:241], v[182:185], v[134:137]
	v_mfma_f32_16x16x32_bf16 v[138:141], v[238:241], v[186:189], v[138:141]
	s_waitcnt lgkmcnt(3)
	v_mfma_f32_16x16x32_bf16 v[142:145], v[238:241], v[190:193], v[142:145]
	s_branch .LBB0_1681
.Lpeel_1681:
	s_waitcnt lgkmcnt(3)
	v_mfma_f32_16x16x32_bf16 v[114:117], v[178:181], v[194:197], v[114:117]
	v_mfma_f32_16x16x32_bf16 v[134:137], v[178:181], v[198:201], v[134:137]
	v_mfma_f32_16x16x32_bf16 v[138:141], v[178:181], v[218:221], v[138:141]
	v_mfma_f32_16x16x32_bf16 v[142:145], v[178:181], v[226:229], v[142:145]
	ds_read_b128 v[202:205], v217 offset:8192
	s_waitcnt lgkmcnt(3)
	v_mfma_f32_16x16x32_bf16 v[174:177], v[182:185], v[226:229], v[174:177]
	v_mfma_f32_16x16x32_bf16 v[170:173], v[182:185], v[218:221], v[170:173]
	v_mfma_f32_16x16x32_bf16 v[166:169], v[182:185], v[198:201], v[166:169]
	v_mfma_f32_16x16x32_bf16 v[162:165], v[182:185], v[194:197], v[162:165]
	v_add_u32_e32 v222, v215, v213
	ds_read_b128 v[238:241], v217 offset:10240
	ds_read_b128 v[178:181], v222 offset:32768
	s_waitcnt lgkmcnt(4)
	v_mfma_f32_16x16x32_bf16 v[146:149], v[186:189], v[194:197], v[146:149]
	v_mfma_f32_16x16x32_bf16 v[150:153], v[186:189], v[198:201], v[150:153]
	v_mfma_f32_16x16x32_bf16 v[154:157], v[186:189], v[218:221], v[154:157]
	v_mfma_f32_16x16x32_bf16 v[158:161], v[186:189], v[226:229], v[158:161]
	ds_read_b128 v[242:245], v217 offset:12288
	ds_read_b128 v[182:185], v222 offset:34816
	s_waitcnt lgkmcnt(5)
	v_mfma_f32_16x16x32_bf16 v[130:133], v[190:193], v[226:229], v[130:133]
	v_mfma_f32_16x16x32_bf16 v[126:129], v[190:193], v[218:221], v[126:129]
	v_mfma_f32_16x16x32_bf16 v[122:125], v[190:193], v[198:201], v[122:125]
	v_mfma_f32_16x16x32_bf16 v[118:121], v[190:193], v[194:197], v[118:121]
	ds_read_b128 v[246:249], v217 offset:14336
	ds_read_b128 v[186:189], v222 offset:36864
	s_waitcnt lgkmcnt(6)
	v_mfma_f32_16x16x32_bf16 v[98:101], v[202:205], v[194:197], v[98:101]
	v_mfma_f32_16x16x32_bf16 v[102:105], v[202:205], v[198:201], v[102:105]
	v_mfma_f32_16x16x32_bf16 v[106:109], v[202:205], v[218:221], v[106:109]
	v_mfma_f32_16x16x32_bf16 v[110:113], v[202:205], v[226:229], v[110:113]
	v_add_u32_e32 v217, v214, v213
	s_waitcnt lgkmcnt(5)
	v_mfma_f32_16x16x32_bf16 v[94:97], v[238:241], v[226:229], v[94:97]
	v_mfma_f32_16x16x32_bf16 v[90:93], v[238:241], v[218:221], v[90:93]
	v_mfma_f32_16x16x32_bf16 v[86:89], v[238:241], v[198:201], v[86:89]
	v_mfma_f32_16x16x32_bf16 v[82:85], v[238:241], v[194:197], v[82:85]
	ds_read_b128 v[238:241], v217
	ds_read_b128 v[190:193], v222 offset:38912
	ds_read_b128 v[202:205], v217 offset:2048
	s_waitcnt lgkmcnt(6)
	v_mfma_f32_16x16x32_bf16 v[66:69], v[242:245], v[194:197], v[66:69]
	v_mfma_f32_16x16x32_bf16 v[70:73], v[242:245], v[198:201], v[70:73]
	v_mfma_f32_16x16x32_bf16 v[74:77], v[242:245], v[218:221], v[74:77]
	v_mfma_f32_16x16x32_bf16 v[78:81], v[242:245], v[226:229], v[78:81]
	s_waitcnt lgkmcnt(4)
	v_mfma_f32_16x16x32_bf16 v[54:57], v[246:249], v[198:201], v[54:57]
	ds_read_b128 v[198:201], v217 offset:4096
	v_mfma_f32_16x16x32_bf16 v[50:53], v[246:249], v[194:197], v[50:53]
	v_mfma_f32_16x16x32_bf16 v[58:61], v[246:249], v[218:221], v[58:61]
	v_mfma_f32_16x16x32_bf16 v[62:65], v[246:249], v[226:229], v[62:65]
	ds_read_b128 v[194:197], v217 offset:6144
	s_waitcnt lgkmcnt(4)
	v_mfma_f32_16x16x32_bf16 v[114:117], v[238:241], v[178:181], v[114:117]
	v_mfma_f32_16x16x32_bf16 v[134:137], v[238:241], v[182:185], v[134:137]
	v_mfma_f32_16x16x32_bf16 v[138:141], v[238:241], v[186:189], v[138:141]
	s_waitcnt lgkmcnt(3)
	v_mfma_f32_16x16x32_bf16 v[142:145], v[238:241], v[190:193], v[142:145]
	s_waitcnt lgkmcnt(2)
	v_mfma_f32_16x16x32_bf16 v[174:177], v[202:205], v[190:193], v[174:177]
	v_mfma_f32_16x16x32_bf16 v[170:173], v[202:205], v[186:189], v[170:173]
	v_mfma_f32_16x16x32_bf16 v[166:169], v[202:205], v[182:185], v[166:169]
	v_mfma_f32_16x16x32_bf16 v[162:165], v[202:205], v[178:181], v[162:165]
	ds_read_b128 v[202:205], v217 offset:8192
	s_waitcnt lgkmcnt(2)
	v_mfma_f32_16x16x32_bf16 v[146:149], v[198:201], v[178:181], v[146:149]
	v_mfma_f32_16x16x32_bf16 v[150:153], v[198:201], v[182:185], v[150:153]
	v_mfma_f32_16x16x32_bf16 v[154:157], v[198:201], v[186:189], v[154:157]
	v_mfma_f32_16x16x32_bf16 v[158:161], v[198:201], v[190:193], v[158:161]
	ds_read_b128 v[198:201], v217 offset:10240
	s_waitcnt lgkmcnt(2)
	v_mfma_f32_16x16x32_bf16 v[130:133], v[194:197], v[190:193], v[130:133]
	v_mfma_f32_16x16x32_bf16 v[126:129], v[194:197], v[186:189], v[126:129]
	v_mfma_f32_16x16x32_bf16 v[122:125], v[194:197], v[182:185], v[122:125]
	v_mfma_f32_16x16x32_bf16 v[118:121], v[194:197], v[178:181], v[118:121]
	ds_read_b128 v[194:197], v217 offset:12288
	s_waitcnt lgkmcnt(2)
	v_mfma_f32_16x16x32_bf16 v[98:101], v[202:205], v[178:181], v[98:101]
	v_mfma_f32_16x16x32_bf16 v[102:105], v[202:205], v[182:185], v[102:105]
	v_mfma_f32_16x16x32_bf16 v[106:109], v[202:205], v[186:189], v[106:109]
	v_mfma_f32_16x16x32_bf16 v[110:113], v[202:205], v[190:193], v[110:113]
	ds_read_b128 v[202:205], v217 offset:14336
	s_waitcnt lgkmcnt(2)
	v_mfma_f32_16x16x32_bf16 v[94:97], v[198:201], v[190:193], v[94:97]
	v_mfma_f32_16x16x32_bf16 v[90:93], v[198:201], v[186:189], v[90:93]
	v_mfma_f32_16x16x32_bf16 v[86:89], v[198:201], v[182:185], v[86:89]
	v_mfma_f32_16x16x32_bf16 v[82:85], v[198:201], v[178:181], v[82:85]
	s_waitcnt lgkmcnt(1)
	v_mfma_f32_16x16x32_bf16 v[66:69], v[194:197], v[178:181], v[66:69]
	v_mfma_f32_16x16x32_bf16 v[70:73], v[194:197], v[182:185], v[70:73]
	v_mfma_f32_16x16x32_bf16 v[74:77], v[194:197], v[186:189], v[74:77]
	v_mfma_f32_16x16x32_bf16 v[78:81], v[194:197], v[190:193], v[78:81]
	s_waitcnt lgkmcnt(0)
	v_mfma_f32_16x16x32_bf16 v[62:65], v[202:205], v[190:193], v[62:65]
	v_mfma_f32_16x16x32_bf16 v[58:61], v[202:205], v[186:189], v[58:61]
	v_mfma_f32_16x16x32_bf16 v[54:57], v[202:205], v[182:185], v[54:57]
	v_mfma_f32_16x16x32_bf16 v[50:53], v[202:205], v[178:181], v[50:53]
	s_setprio 0
	s_branch .LBB0_1686

.LBB0_1814:
	s_add_i32 s20, s20, 64
	s_waitcnt lgkmcnt(2)
	v_mfma_f32_16x16x32_bf16 v[162:165], v[202:205], v[178:181], v[162:165]
	v_mfma_f32_16x16x32_bf16 v[154:157], v[202:205], v[182:185], v[154:157]
	v_mfma_f32_16x16x32_bf16 v[118:121], v[202:205], v[186:189], v[118:121]
	v_mfma_f32_16x16x32_bf16 v[106:109], v[202:205], v[190:193], v[106:109]
	ds_read_b128 v[202:205], v216 offset:8192
	s_waitcnt lgkmcnt(2)
	v_mfma_f32_16x16x32_bf16 v[82:85], v[198:201], v[190:193], v[82:85]
	v_mfma_f32_16x16x32_bf16 v[86:89], v[198:201], v[186:189], v[86:89]
	v_mfma_f32_16x16x32_bf16 v[90:93], v[198:201], v[182:185], v[90:93]
	v_mfma_f32_16x16x32_bf16 v[94:97], v[198:201], v[178:181], v[94:97]
	ds_read_b128 v[198:201], v216 offset:10240
	s_waitcnt lgkmcnt(2)
	v_mfma_f32_16x16x32_bf16 v[78:81], v[194:197], v[178:181], v[78:81]
	v_mfma_f32_16x16x32_bf16 v[74:77], v[194:197], v[182:185], v[74:77]
	v_mfma_f32_16x16x32_bf16 v[70:73], v[194:197], v[186:189], v[70:73]
	v_mfma_f32_16x16x32_bf16 v[66:69], v[194:197], v[190:193], v[66:69]
	ds_read_b128 v[194:197], v216 offset:12288
	s_waitcnt lgkmcnt(2)
	v_mfma_f32_16x16x32_bf16 v[50:53], v[202:205], v[190:193], v[50:53]
	v_mfma_f32_16x16x32_bf16 v[54:57], v[202:205], v[186:189], v[54:57]
	v_mfma_f32_16x16x32_bf16 v[58:61], v[202:205], v[182:185], v[58:61]
	v_mfma_f32_16x16x32_bf16 v[62:65], v[202:205], v[178:181], v[62:65]
	ds_read_b128 v[202:205], v216 offset:14336
	s_waitcnt lgkmcnt(2)
	v_mfma_f32_16x16x32_bf16 v[46:49], v[198:201], v[178:181], v[46:49]
	v_mfma_f32_16x16x32_bf16 v[42:45], v[198:201], v[182:185], v[42:45]
	v_mfma_f32_16x16x32_bf16 v[38:41], v[198:201], v[186:189], v[38:41]
	v_mfma_f32_16x16x32_bf16 v[34:37], v[198:201], v[190:193], v[34:37]
	s_waitcnt lgkmcnt(1)
	v_mfma_f32_16x16x32_bf16 v[6:9], v[194:197], v[190:193], v[6:9]
	v_mfma_f32_16x16x32_bf16 v[18:21], v[194:197], v[186:189], v[18:21]
	v_mfma_f32_16x16x32_bf16 v[26:29], v[194:197], v[182:185], v[26:29]
	v_mfma_f32_16x16x32_bf16 v[30:33], v[194:197], v[178:181], v[30:33]
	s_waitcnt lgkmcnt(0)
	v_mfma_f32_16x16x32_bf16 v[22:25], v[202:205], v[178:181], v[22:25]
	v_mfma_f32_16x16x32_bf16 v[14:17], v[202:205], v[182:185], v[14:17]
	v_mfma_f32_16x16x32_bf16 v[10:13], v[202:205], v[186:189], v[10:13]
	v_mfma_f32_16x16x32_bf16 v[2:5], v[202:205], v[190:193], v[2:5]
	s_setprio 0
	s_add_u32 s36, s36, 0x80
	s_addc_u32 s37, s37, 0
	s_add_u32 s38, s38, 0x80
	s_addc_u32 s39, s39, 0
	s_and_b64 vcc, exec, s[40:41]
	s_cbranch_vccnz .LBB0_1821

.LBB0_1817:
	s_waitcnt lgkmcnt(3)
	v_mfma_f32_16x16x32_bf16 v[158:161], v[178:181], v[226:229], v[158:161]
	v_mfma_f32_16x16x32_bf16 v[166:169], v[178:181], v[218:221], v[166:169]
	v_mfma_f32_16x16x32_bf16 v[170:173], v[178:181], v[198:201], v[170:173]
	v_mfma_f32_16x16x32_bf16 v[174:177], v[178:181], v[194:197], v[174:177]
	s_add_u32 s100, s36, 0xc5cc000
	s_addc_u32 s101, s37, 0
	global_load_dwordx4 v[98:101], v208, s[100:101] offset:128
	v_add_u32_e32 v102, 0x2c000, v208
	global_load_dwordx4 v[102:105], v102, s[100:101] offset:128
	ds_read_b128 v[202:205], v216 offset:8192
	s_waitcnt lgkmcnt(3)
	v_mfma_f32_16x16x32_bf16 v[162:165], v[182:185], v[194:197], v[162:165]
	v_mfma_f32_16x16x32_bf16 v[154:157], v[182:185], v[198:201], v[154:157]
	v_mfma_f32_16x16x32_bf16 v[118:121], v[182:185], v[218:221], v[118:121]
	v_mfma_f32_16x16x32_bf16 v[106:109], v[182:185], v[226:229], v[106:109]
	v_add_u32_e32 v110, 0x58000, v208
	global_load_dwordx4 v[110:113], v110, s[100:101] offset:128
	v_add_u32_e32 v114, 0x84000, v208
	global_load_dwordx4 v[114:117], v114, s[100:101] offset:128
	v_add_u32_e32 v217, v214, v212
	ds_read_b128 v[238:241], v216 offset:10240
	ds_read_b128 v[178:181], v217 offset:32768
	s_waitcnt lgkmcnt(4)
	v_mfma_f32_16x16x32_bf16 v[82:85], v[186:189], v[226:229], v[82:85]
	v_mfma_f32_16x16x32_bf16 v[86:89], v[186:189], v[218:221], v[86:89]
	v_mfma_f32_16x16x32_bf16 v[90:93], v[186:189], v[198:201], v[90:93]
	v_mfma_f32_16x16x32_bf16 v[94:97], v[186:189], v[194:197], v[94:97]
	v_add_u32_e32 v122, 0xb0000, v208
	global_load_dwordx4 v[122:125], v122, s[100:101] offset:128
	v_add_u32_e32 v130, 0xdc000, v208
	global_load_dwordx4 v[130:133], v130, s[100:101] offset:128
	ds_read_b128 v[242:245], v216 offset:12288
	ds_read_b128 v[182:185], v217 offset:34816
	s_waitcnt lgkmcnt(5)
	v_mfma_f32_16x16x32_bf16 v[78:81], v[190:193], v[194:197], v[78:81]
	v_mfma_f32_16x16x32_bf16 v[74:77], v[190:193], v[198:201], v[74:77]
	v_mfma_f32_16x16x32_bf16 v[70:73], v[190:193], v[218:221], v[70:73]
	v_mfma_f32_16x16x32_bf16 v[66:69], v[190:193], v[226:229], v[66:69]
	v_add_u32_e32 v138, 0x108000, v208
	global_load_dwordx4 v[138:141], v138, s[100:101] offset:128
	v_add_u32_e32 v146, 0x134000, v208
	global_load_dwordx4 v[146:149], v146, s[100:101] offset:128
	ds_read_b128 v[246:249], v216 offset:14336
	ds_read_b128 v[186:189], v217 offset:36864
	s_waitcnt lgkmcnt(6)
	v_mfma_f32_16x16x32_bf16 v[50:53], v[202:205], v[226:229], v[50:53]
	v_mfma_f32_16x16x32_bf16 v[54:57], v[202:205], v[218:221], v[54:57]
	v_mfma_f32_16x16x32_bf16 v[58:61], v[202:205], v[198:201], v[58:61]
	v_mfma_f32_16x16x32_bf16 v[62:65], v[202:205], v[194:197], v[62:65]
	s_add_u32 s100, s38, 0xc04c000
	s_addc_u32 s101, s39, 0
	global_load_dwordx4 v[126:129], v208, s[100:101] offset:128
	v_add_u32_e32 v134, 0x2c000, v208
	global_load_dwordx4 v[134:137], v134, s[100:101] offset:128
	v_add_u32_e32 v216, v213, v212
	s_waitcnt lgkmcnt(5)
	v_mfma_f32_16x16x32_bf16 v[46:49], v[238:241], v[194:197], v[46:49]
	v_mfma_f32_16x16x32_bf16 v[42:45], v[238:241], v[198:201], v[42:45]
	v_mfma_f32_16x16x32_bf16 v[38:41], v[238:241], v[218:221], v[38:41]
	v_mfma_f32_16x16x32_bf16 v[34:37], v[238:241], v[226:229], v[34:37]
	v_add_u32_e32 v142, 0x58000, v208
	global_load_dwordx4 v[142:145], v142, s[100:101] offset:128
	v_add_u32_e32 v150, 0x84000, v208
	global_load_dwordx4 v[150:153], v150, s[100:101] offset:128
	ds_read_b128 v[238:241], v216
	ds_read_b128 v[190:193], v217 offset:38912
	ds_read_b128 v[202:205], v216 offset:2048
	s_waitcnt lgkmcnt(6)
	v_mfma_f32_16x16x32_bf16 v[6:9], v[242:245], v[226:229], v[6:9]
	v_mfma_f32_16x16x32_bf16 v[18:21], v[242:245], v[218:221], v[18:21]
	v_mfma_f32_16x16x32_bf16 v[26:29], v[242:245], v[198:201], v[26:29]
	v_mfma_f32_16x16x32_bf16 v[30:33], v[242:245], v[194:197], v[30:33]
	s_waitcnt lgkmcnt(4)
	v_mfma_f32_16x16x32_bf16 v[14:17], v[246:249], v[198:201], v[14:17]
	ds_read_b128 v[198:201], v216 offset:4096
	v_mfma_f32_16x16x32_bf16 v[22:25], v[246:249], v[194:197], v[22:25]
	v_mfma_f32_16x16x32_bf16 v[10:13], v[246:249], v[218:221], v[10:13]
	v_mfma_f32_16x16x32_bf16 v[2:5], v[246:249], v[226:229], v[2:5]
	ds_read_b128 v[194:197], v216 offset:6144
	s_waitcnt lgkmcnt(4)
	v_mfma_f32_16x16x32_bf16 v[174:177], v[238:241], v[178:181], v[174:177]
	v_mfma_f32_16x16x32_bf16 v[170:173], v[238:241], v[182:185], v[170:173]
	v_mfma_f32_16x16x32_bf16 v[166:169], v[238:241], v[186:189], v[166:169]
	s_waitcnt lgkmcnt(3)
	v_mfma_f32_16x16x32_bf16 v[158:161], v[238:241], v[190:193], v[158:161]
	s_branch .LBB0_1814
.Lpeel_1814:
	s_waitcnt lgkmcnt(3)
	v_mfma_f32_16x16x32_bf16 v[174:177], v[178:181], v[194:197], v[174:177]
	v_mfma_f32_16x16x32_bf16 v[170:173], v[178:181], v[198:201], v[170:173]
	v_mfma_f32_16x16x32_bf16 v[166:169], v[178:181], v[218:221], v[166:169]
	v_mfma_f32_16x16x32_bf16 v[158:161], v[178:181], v[226:229], v[158:161]
	ds_read_b128 v[202:205], v216 offset:8192
	s_waitcnt lgkmcnt(3)
	v_mfma_f32_16x16x32_bf16 v[106:109], v[182:185], v[226:229], v[106:109]
	v_mfma_f32_16x16x32_bf16 v[118:121], v[182:185], v[218:221], v[118:121]
	v_mfma_f32_16x16x32_bf16 v[154:157], v[182:185], v[198:201], v[154:157]
	v_mfma_f32_16x16x32_bf16 v[162:165], v[182:185], v[194:197], v[162:165]
	v_add_u32_e32 v217, v214, v212
	ds_read_b128 v[238:241], v216 offset:10240
	ds_read_b128 v[178:181], v217 offset:32768
	s_waitcnt lgkmcnt(4)
	v_mfma_f32_16x16x32_bf16 v[94:97], v[186:189], v[194:197], v[94:97]
	v_mfma_f32_16x16x32_bf16 v[90:93], v[186:189], v[198:201], v[90:93]
	v_mfma_f32_16x16x32_bf16 v[86:89], v[186:189], v[218:221], v[86:89]
	v_mfma_f32_16x16x32_bf16 v[82:85], v[186:189], v[226:229], v[82:85]
	ds_read_b128 v[242:245], v216 offset:12288
	ds_read_b128 v[182:185], v217 offset:34816
	s_waitcnt lgkmcnt(5)
	v_mfma_f32_16x16x32_bf16 v[66:69], v[190:193], v[226:229], v[66:69]
	v_mfma_f32_16x16x32_bf16 v[70:73], v[190:193], v[218:221], v[70:73]
	v_mfma_f32_16x16x32_bf16 v[74:77], v[190:193], v[198:201], v[74:77]
	v_mfma_f32_16x16x32_bf16 v[78:81], v[190:193], v[194:197], v[78:81]
	ds_read_b128 v[246:249], v216 offset:14336
	ds_read_b128 v[186:189], v217 offset:36864
	s_waitcnt lgkmcnt(6)
	v_mfma_f32_16x16x32_bf16 v[62:65], v[202:205], v[194:197], v[62:65]
	v_mfma_f32_16x16x32_bf16 v[58:61], v[202:205], v[198:201], v[58:61]
	v_mfma_f32_16x16x32_bf16 v[54:57], v[202:205], v[218:221], v[54:57]
	v_mfma_f32_16x16x32_bf16 v[50:53], v[202:205], v[226:229], v[50:53]
	v_add_u32_e32 v216, v213, v212
	s_waitcnt lgkmcnt(5)
	v_mfma_f32_16x16x32_bf16 v[34:37], v[238:241], v[226:229], v[34:37]
	v_mfma_f32_16x16x32_bf16 v[38:41], v[238:241], v[218:221], v[38:41]
	v_mfma_f32_16x16x32_bf16 v[42:45], v[238:241], v[198:201], v[42:45]
	v_mfma_f32_16x16x32_bf16 v[46:49], v[238:241], v[194:197], v[46:49]
	ds_read_b128 v[238:241], v216
	ds_read_b128 v[190:193], v217 offset:38912
	ds_read_b128 v[202:205], v216 offset:2048
	s_waitcnt lgkmcnt(6)
	v_mfma_f32_16x16x32_bf16 v[30:33], v[242:245], v[194:197], v[30:33]
	v_mfma_f32_16x16x32_bf16 v[26:29], v[242:245], v[198:201], v[26:29]
	v_mfma_f32_16x16x32_bf16 v[18:21], v[242:245], v[218:221], v[18:21]
	v_mfma_f32_16x16x32_bf16 v[6:9], v[242:245], v[226:229], v[6:9]
	s_waitcnt lgkmcnt(4)
	v_mfma_f32_16x16x32_bf16 v[14:17], v[246:249], v[198:201], v[14:17]
	ds_read_b128 v[198:201], v216 offset:4096
	v_mfma_f32_16x16x32_bf16 v[22:25], v[246:249], v[194:197], v[22:25]
	v_mfma_f32_16x16x32_bf16 v[10:13], v[246:249], v[218:221], v[10:13]
	v_mfma_f32_16x16x32_bf16 v[2:5], v[246:249], v[226:229], v[2:5]
	ds_read_b128 v[194:197], v216 offset:6144
	s_waitcnt lgkmcnt(4)
	v_mfma_f32_16x16x32_bf16 v[174:177], v[238:241], v[178:181], v[174:177]
	v_mfma_f32_16x16x32_bf16 v[170:173], v[238:241], v[182:185], v[170:173]
	v_mfma_f32_16x16x32_bf16 v[166:169], v[238:241], v[186:189], v[166:169]
	s_waitcnt lgkmcnt(3)
	v_mfma_f32_16x16x32_bf16 v[158:161], v[238:241], v[190:193], v[158:161]
	s_add_i32 s20, s20, 64
	s_waitcnt lgkmcnt(2)
	v_mfma_f32_16x16x32_bf16 v[106:109], v[202:205], v[190:193], v[106:109]
	v_mfma_f32_16x16x32_bf16 v[118:121], v[202:205], v[186:189], v[118:121]
	v_mfma_f32_16x16x32_bf16 v[154:157], v[202:205], v[182:185], v[154:157]
	v_mfma_f32_16x16x32_bf16 v[162:165], v[202:205], v[178:181], v[162:165]
	ds_read_b128 v[202:205], v216 offset:8192
	s_waitcnt lgkmcnt(2)
	v_mfma_f32_16x16x32_bf16 v[94:97], v[198:201], v[178:181], v[94:97]
	v_mfma_f32_16x16x32_bf16 v[90:93], v[198:201], v[182:185], v[90:93]
	v_mfma_f32_16x16x32_bf16 v[86:89], v[198:201], v[186:189], v[86:89]
	v_mfma_f32_16x16x32_bf16 v[82:85], v[198:201], v[190:193], v[82:85]
	ds_read_b128 v[198:201], v216 offset:10240
	s_waitcnt lgkmcnt(2)
	v_mfma_f32_16x16x32_bf16 v[66:69], v[194:197], v[190:193], v[66:69]
	v_mfma_f32_16x16x32_bf16 v[70:73], v[194:197], v[186:189], v[70:73]
	v_mfma_f32_16x16x32_bf16 v[74:77], v[194:197], v[182:185], v[74:77]
	v_mfma_f32_16x16x32_bf16 v[78:81], v[194:197], v[178:181], v[78:81]
	ds_read_b128 v[194:197], v216 offset:12288
	s_waitcnt lgkmcnt(2)
	v_mfma_f32_16x16x32_bf16 v[62:65], v[202:205], v[178:181], v[62:65]
	v_mfma_f32_16x16x32_bf16 v[58:61], v[202:205], v[182:185], v[58:61]
	v_mfma_f32_16x16x32_bf16 v[54:57], v[202:205], v[186:189], v[54:57]
	v_mfma_f32_16x16x32_bf16 v[50:53], v[202:205], v[190:193], v[50:53]
	ds_read_b128 v[202:205], v216 offset:14336
	s_waitcnt lgkmcnt(2)
	v_mfma_f32_16x16x32_bf16 v[34:37], v[198:201], v[190:193], v[34:37]
	v_mfma_f32_16x16x32_bf16 v[38:41], v[198:201], v[186:189], v[38:41]
	v_mfma_f32_16x16x32_bf16 v[42:45], v[198:201], v[182:185], v[42:45]
	v_mfma_f32_16x16x32_bf16 v[46:49], v[198:201], v[178:181], v[46:49]
	s_waitcnt lgkmcnt(1)
	v_mfma_f32_16x16x32_bf16 v[30:33], v[194:197], v[178:181], v[30:33]
	v_mfma_f32_16x16x32_bf16 v[26:29], v[194:197], v[182:185], v[26:29]
	v_mfma_f32_16x16x32_bf16 v[18:21], v[194:197], v[186:189], v[18:21]
	v_mfma_f32_16x16x32_bf16 v[6:9], v[194:197], v[190:193], v[6:9]
	s_waitcnt lgkmcnt(0)
	v_mfma_f32_16x16x32_bf16 v[2:5], v[202:205], v[190:193], v[2:5]
	v_mfma_f32_16x16x32_bf16 v[10:13], v[202:205], v[186:189], v[10:13]
	v_mfma_f32_16x16x32_bf16 v[14:17], v[202:205], v[182:185], v[14:17]
	v_mfma_f32_16x16x32_bf16 v[22:25], v[202:205], v[178:181], v[22:25]
	s_setprio 0
	s_branch .LBB0_1821
